# loop-edge edits: scalar has_next test when the grid is 256 (no VALU compare on the unit-loop head), K-loop header skips the hook test chain on non-last iterations
# speedup vs baseline: 1.0124x; 1.0055x over previous
; template <int MODE> __device__ __forceinline__ UD decode(int j) { UD x; x.u = j & 7; int bh; if (MODE == 1) { bh = j >> 4; x.br = 1 + ((j >> 3) & 1); } else { bh = j >> 3; x.br = 0; } x.b = bh / NH; x.h = bh % NH; return x; }
;     __host__ __device__ bool next(int i, Unit& u) const {
;         const long L = (long)i * G + c; if (i >= imax || L >= nwg) return false;
;         decode(L, u); u.par = i & 1; u.roff = 0; return true;
; template <class Epi, class Sched, bool ALIGN_EPI = false, bool SP2 = false, bool HALFM = false>
; __device__ __forceinline__ void gemm_phase(PG8_LAS unsigned char* lds, const Gemm g, const Sched& S, const Epi& E) {
;     ...
;         const bool has_next = S.next(ui + 1, nxt);
.LBB0_175:
	s_mov_b32 s9, s53
	s_add_i32 s53, s53, 1
	s_cmpk_lg_u32 s72, 0x100
	s_cbranch_scc1 .Lgu_hasnext_generic
	s_lshl_b32 s12, s53, 8
	s_add_u32 s12, s12, s33
	s_mov_b32 s13, 0
	s_cmp_gt_u32 s12, 0x57f
	s_cselect_b64 s[18:19], -1, 0
	s_cbranch_scc1 .LBB0_177
	s_branch .Lgu_decode_fast
.Lgu_hasnext_generic:
	s_mul_i32 s11, s53, s39
	s_mul_hi_u32 s12, s53, s72
	s_add_i32 s11, s12, s11
	s_mul_i32 s12, s53, s72
	s_add_u32 s12, s12, s33
	s_addc_u32 s13, s11, s38
	s_cmp_gt_u32 s9, 0x3ffffffe
	s_cselect_b64 s[14:15], -1, 0
	v_cmp_gt_i64_e32 vcc, s[12:13], v[154:155]
	s_or_b64 s[18:19], s[14:15], vcc
	s_and_b64 vcc, exec, s[18:19]
	s_cbranch_vccnz .LBB0_177
	s_cmpk_lg_u32 s72, 0x100
	s_cbranch_scc1 .Lgu_decode_generic
.Lgu_decode_fast:
	s_mov_b32 s10, s57
	s_add_i32 s8, s56, 4
	s_and_b32 s54, s53, 1
	s_branch .LBB0_177

; template <class Epi, class Sched, bool ALIGN_EPI = false, bool SP2 = false, bool HALFM = false>
; __device__ __forceinline__ void gemm_phase(PG8_LAS unsigned char* lds, const Gemm g, const Sched& S, const Epi& E) {
;     ...
;             const bool last = (t == nt - 2);
;     ...
;             if (last && has_next) S.a_ready(nxt);
; __device__ __forceinline__ float rinv_of(const float* P, int row) {
;     const f32x4* p = (const f32x4*)(P + (size_t)row * 16);
;     const f32x4 a = p[0], b = p[1], c = p[2], d = p[3];
;     const float s = ((a[0] + a[1]) + (a[2] + a[3])) + ((b[0] + b[1]) + (b[2] + b[3])) + ((c[0] + c[1]) + (c[2] + c[3])) + ((d[0] + d[1]) + (d[2] + d[3]));
;     return __builtin_amdgcn_rsqf(s * (1.0f / DM) + NORM_EPS);
; }
;     __device__ __forceinline__ void a_ready(const Unit& u) const { if (u.pm == pm0) return; int t = threadIdx.x; asm volatile("" : "+v"(t)); if (t < 256 - u.roff) tab[u.par * 256 + t] = rinv_of(P, u.pm * BM + u.roff + t); }
.LBB0_180:
	s_cmp_lg_u32 s64, 12
	s_cselect_b64 s[24:25], -1, 0
	s_cbranch_scc1 .LBB0_179
	s_or_b64 s[26:27], s[18:19], s[24:25]
	s_or_b64 s[26:27], s[26:27], s[20:21]
	s_and_b64 vcc, exec, s[26:27]
	s_cbranch_vccnz .LBB0_179
	v_mov_b32_e32 v140, v190
	s_nop 0
	v_cmp_gt_i32_e32 vcc, s3, v140
	s_and_saveexec_b64 s[26:27], vcc
	s_cbranch_execz .LBB0_178
	v_add_u32_e32 v148, s60, v140
	v_ashrrev_i32_e32 v149, 31, v148
	v_lshlrev_b64 v[148:149], 6, v[148:149]
	v_lshl_add_u64 v[152:153], s[36:37], 0, v[148:149]
	global_load_dwordx4 v[148:151], v[152:153], off offset:48
	global_load_dwordx4 v[160:163], v[152:153], off offset:32
	global_load_dwordx4 v[164:167], v[152:153], off offset:16
	global_load_dwordx4 v[168:171], v[152:153], off
	v_lshl_add_u32 v140, v140, 2, s61
	s_waitcnt vmcnt(0)
	v_add_f32_e32 v160, v160, v161
	v_add_f32_e32 v162, v162, v163
	v_mov_b32_e32 v152, v169
	v_mov_b32_e32 v153, v170
	v_mov_b32_e32 v169, v171
	v_pk_add_f32 v[152:153], v[152:153], v[168:169]
	v_mov_b32_e32 v168, v165
	v_mov_b32_e32 v169, v166
	v_mov_b32_e32 v165, v167
	v_pk_add_f32 v[164:165], v[168:169], v[164:165]
	v_pk_add_f32 v[152:153], v[152:153], v[152:153] op_sel:[0,1] op_sel_hi:[1,0]
	v_pk_add_f32 v[164:165], v[164:165], v[164:165] op_sel:[0,1] op_sel_hi:[1,0]
	v_mov_b32_e32 v153, v148
	v_mov_b32_e32 v165, v149
	v_mov_b32_e32 v161, v150
	v_mov_b32_e32 v163, v151
	v_pk_add_f32 v[148:149], v[152:153], v[164:165]
	v_pk_add_f32 v[150:151], v[160:161], v[162:163]
	s_nop 0
	v_pk_add_f32 v[148:149], v[148:149], v[150:151]
	s_nop 0
	v_add_f32_e32 v141, v148, v149
	v_fmamk_f32 v141, v141, 0x3a800000, v195
	v_rsq_f32_e32 v141, v141
	ds_write_b32 v140, v141
	s_branch .LBB0_178

; template <int MODE> __device__ __forceinline__ UD decode(int j) { UD x; x.u = j & 7; int bh; if (MODE == 1) { bh = j >> 4; x.br = 1 + ((j >> 3) & 1); } else { bh = j >> 3; x.br = 0; } x.b = bh / NH; x.h = bh % NH; return x; }
;     __host__ __device__ bool next(int i, Unit& u) const {
;         const long L = (long)i * G + c; if (i >= imax || L >= nwg) return false;
;         decode(L, u); u.par = i & 1; u.roff = 0; return true;
; template <class Epi, class Sched, bool ALIGN_EPI = false, bool SP2 = false, bool HALFM = false>
; __device__ __forceinline__ void gemm_phase(PG8_LAS unsigned char* lds, const Gemm g, const Sched& S, const Epi& E) {
;     ...
;         const bool has_next = S.next(ui + 1, nxt);
.LBB0_409:
	s_mov_b32 s0, s55
	s_add_i32 s55, s55, 1
	s_cmpk_lg_u32 s72, 0x100
	s_cbranch_scc1 .Lwi_hasnext_generic
	s_lshl_b32 s16, s55, 8
	s_add_u32 s16, s16, s33
	s_mov_b32 s17, 0
	s_cmp_gt_u32 s16, 0x27f
	s_cselect_b64 s[0:1], -1, 0
	s_cbranch_scc1 .LBB0_411
	s_branch .Lwi_decode_fast
.Lwi_hasnext_generic:
	s_mul_i32 s1, s55, s39
	s_mul_hi_u32 s13, s55, s72
	s_add_i32 s13, s13, s1
	s_mul_i32 s1, s55, s72
	s_add_u32 s16, s1, s33
	s_addc_u32 s17, s13, s38
	s_cmp_gt_u32 s0, 0x3ffffffe
	s_cselect_b64 s[0:1], -1, 0
	v_cmp_gt_i64_e32 vcc, s[16:17], v[158:159]
	s_or_b64 s[0:1], s[0:1], vcc
	s_and_b64 vcc, exec, s[0:1]
	s_cbranch_vccnz .LBB0_411
	s_cmpk_lg_u32 s72, 0x100
	s_cbranch_scc1 .Lwi_decode_generic
.Lwi_decode_fast:
	s_mov_b32 s14, s58
	s_add_i32 s12, s59, 4
	s_and_b32 s56, s55, 1
	s_branch .LBB0_411
